# hand-written norm1/norm2 phases: three rows per wave, all row and modulation-vector loads issued up front, DPP row reduction
# speedup vs baseline: 1.0090x; 1.0090x over previous
.Lssd_back:
	s_cmp_eq_u32 s5, 0
	s_cbranch_scc1 .Lnm0_entry
	s_cmp_eq_u32 s5, 7
	s_cbranch_scc1 .Lnm1_entry
	s_cmp_eq_u32 s5, 3
	s_cbranch_scc1 .Lsp3_entry

.Lnm0_entry:
	v_and_b32_e32 v134, 63, v206
	v_lshrrev_b32_e32 v135, 6, v206
	v_lshlrev_b32_e32 v132, 4, v134
	v_readfirstlane_b32 s40, v135
	s_lshl_b32 s41, s63, 3
	s_add_u32 s41, s41, s40
	s_mov_b32 s44, s16
	s_mov_b32 s45, s17
	s_mov_b32 s46, s30
	s_mov_b32 s47, s31
	s_lshl_b32 s42, s41, 12
	s_add_u32 s48, s44, s42
	s_addc_u32 s49, s45, 0
	s_add_u32 s50, s48, 0x800000
	s_addc_u32 s51, s49, 0
	s_add_u32 s52, s46, s42
	s_addc_u32 s53, s47, 0
	global_load_dwordx4 v[4:7], v132, s[48:49]
	global_load_dwordx4 v[8:11], v132, s[48:49] offset:1024
	global_load_dwordx4 v[12:15], v132, s[48:49] offset:2048
	global_load_dwordx4 v[16:19], v132, s[48:49] offset:3072
	global_load_dwordx4 v[20:23], v132, s[50:51]
	global_load_dwordx4 v[24:27], v132, s[50:51] offset:1024
	global_load_dwordx4 v[28:31], v132, s[50:51] offset:2048
	global_load_dwordx4 v[32:35], v132, s[50:51] offset:3072
	global_load_dwordx4 v[36:39], v132, s[52:53]
	global_load_dwordx4 v[40:43], v132, s[52:53] offset:1024
	global_load_dwordx4 v[44:47], v132, s[52:53] offset:2048
	global_load_dwordx4 v[48:51], v132, s[52:53] offset:3072
	v_readlane_b32 s54, v237, 11
	v_readlane_b32 s55, v237, 12
	s_lshl_b32 s42, s36, 12
	s_add_u32 s54, s54, s42
	s_addc_u32 s55, s55, 0
	global_load_dwordx4 v[52:55], v132, s[54:55]
	global_load_dwordx4 v[56:59], v132, s[54:55] offset:1024
	global_load_dwordx4 v[60:63], v132, s[54:55] offset:2048
	global_load_dwordx4 v[64:67], v132, s[54:55] offset:3072
	s_mul_i32 s42, s36, 0x12000
	s_add_u32 s42, s42, 0x2e00000
	s_add_u32 s56, s96, s42
	s_addc_u32 s57, s97, 0
	s_lshr_b32 s42, s41, 10
	s_add_u32 s42, s42, 1
	s_mul_i32 s42, s42, 0x6000
	s_add_u32 s58, s56, s42
	s_addc_u32 s59, s57, 0
	global_load_dwordx4 v[68:71], v132, s[56:57]
	global_load_dwordx4 v[72:75], v132, s[56:57] offset:1024
	global_load_dwordx4 v[76:79], v132, s[56:57] offset:2048
	global_load_dwordx4 v[80:83], v132, s[56:57] offset:3072
	s_add_u32 s56, s56, 0x1000
	s_addc_u32 s57, s57, 0
	global_load_dwordx4 v[100:103], v132, s[56:57]
	global_load_dwordx4 v[104:107], v132, s[56:57] offset:1024
	global_load_dwordx4 v[108:111], v132, s[56:57] offset:2048
	global_load_dwordx4 v[112:115], v132, s[56:57] offset:3072
	global_load_dwordx4 v[84:87], v132, s[58:59]
	global_load_dwordx4 v[88:91], v132, s[58:59] offset:1024
	global_load_dwordx4 v[92:95], v132, s[58:59] offset:2048
	global_load_dwordx4 v[96:99], v132, s[58:59] offset:3072
	s_add_u32 s58, s58, 0x1000
	s_addc_u32 s59, s59, 0
	global_load_dwordx4 v[116:119], v132, s[58:59]
	global_load_dwordx4 v[120:123], v132, s[58:59] offset:1024
	global_load_dwordx4 v[124:127], v132, s[58:59] offset:2048
	global_load_dwordx4 v[128:131], v132, s[58:59] offset:3072
	v_lshlrev_b32_e32 v137, 3, v134
	s_lshl_b32 s42, s41, 11
	s_add_u32 s42, s42, 0x2e24000
	s_add_u32 s48, s96, s42
	s_addc_u32 s49, s97, 0
	s_waitcnt vmcnt(28)
	v_mul_f32_e32 v133, v4, v4
	v_fmac_f32_e32 v133, v5, v5
	v_fmac_f32_e32 v133, v6, v6
	v_fmac_f32_e32 v133, v7, v7
	v_fmac_f32_e32 v133, v8, v8
	v_fmac_f32_e32 v133, v9, v9
	v_fmac_f32_e32 v133, v10, v10
	v_fmac_f32_e32 v133, v11, v11
	v_fmac_f32_e32 v133, v12, v12
	v_fmac_f32_e32 v133, v13, v13
	v_fmac_f32_e32 v133, v14, v14
	v_fmac_f32_e32 v133, v15, v15
	v_fmac_f32_e32 v133, v16, v16
	v_fmac_f32_e32 v133, v17, v17
	v_fmac_f32_e32 v133, v18, v18
	v_fmac_f32_e32 v133, v19, v19
	s_nop 1
	v_add_f32_dpp v133, v133, v133 row_shr:1 row_mask:0xf bank_mask:0xf bound_ctrl:0
	s_nop 1
	v_add_f32_dpp v133, v133, v133 row_shr:2 row_mask:0xf bank_mask:0xf bound_ctrl:0
	s_nop 1
	v_add_f32_dpp v133, v133, v133 row_shr:4 row_mask:0xf bank_mask:0xf bound_ctrl:0
	s_nop 1
	v_add_f32_dpp v133, v133, v133 row_shr:8 row_mask:0xf bank_mask:0xf bound_ctrl:0
	s_nop 1
	v_readlane_b32 s35, v133, 15
	v_readlane_b32 s42, v133, 31
	v_readlane_b32 s43, v133, 47
	v_readlane_b32 s54, v133, 63
	v_mov_b32_e32 v135, s35
	v_add_f32_e32 v135, s42, v135
	v_add_f32_e32 v135, s43, v135
	v_add_f32_e32 v135, s54, v135
	v_mov_b32_e32 v136, 0x358637bd
	v_fmac_f32_e32 v136, 0x3a800000, v135
	v_rsq_f32_e32 v136, v136
	s_nop 0
	s_waitcnt vmcnt(0)
	v_add_f32_e32 v100, 1.0, v100
	v_add_f32_e32 v101, 1.0, v101
	v_add_f32_e32 v102, 1.0, v102
	v_add_f32_e32 v103, 1.0, v103
	v_add_f32_e32 v104, 1.0, v104
	v_add_f32_e32 v105, 1.0, v105
	v_add_f32_e32 v106, 1.0, v106
	v_add_f32_e32 v107, 1.0, v107
	v_add_f32_e32 v108, 1.0, v108
	v_add_f32_e32 v109, 1.0, v109
	v_add_f32_e32 v110, 1.0, v110
	v_add_f32_e32 v111, 1.0, v111
	v_add_f32_e32 v112, 1.0, v112
	v_add_f32_e32 v113, 1.0, v113
	v_add_f32_e32 v114, 1.0, v114
	v_add_f32_e32 v115, 1.0, v115
	v_add_f32_e32 v116, 1.0, v116
	v_add_f32_e32 v117, 1.0, v117
	v_add_f32_e32 v118, 1.0, v118
	v_add_f32_e32 v119, 1.0, v119
	v_add_f32_e32 v120, 1.0, v120
	v_add_f32_e32 v121, 1.0, v121
	v_add_f32_e32 v122, 1.0, v122
	v_add_f32_e32 v123, 1.0, v123
	v_add_f32_e32 v124, 1.0, v124
	v_add_f32_e32 v125, 1.0, v125
	v_add_f32_e32 v126, 1.0, v126
	v_add_f32_e32 v127, 1.0, v127
	v_add_f32_e32 v128, 1.0, v128
	v_add_f32_e32 v129, 1.0, v129
	v_add_f32_e32 v130, 1.0, v130
	v_add_f32_e32 v131, 1.0, v131
	v_mul_f32_e32 v4, v4, v136
	v_mul_f32_e32 v4, v4, v52
	v_fma_f32 v4, v4, v100, v68
	v_mul_f32_e32 v5, v5, v136
	v_mul_f32_e32 v5, v5, v53
	v_fma_f32 v5, v5, v101, v69
	v_mul_f32_e32 v6, v6, v136
	v_mul_f32_e32 v6, v6, v54
	v_fma_f32 v6, v6, v102, v70
	v_mul_f32_e32 v7, v7, v136
	v_mul_f32_e32 v7, v7, v55
	v_fma_f32 v7, v7, v103, v71
	v_cvt_pk_bf16_f32 v138, v4, v5
	v_cvt_pk_bf16_f32 v139, v6, v7
	global_store_dwordx2 v137, v[138:139], s[48:49] offset:0
	v_mul_f32_e32 v8, v8, v136
	v_mul_f32_e32 v8, v8, v56
	v_fma_f32 v8, v8, v104, v72
	v_mul_f32_e32 v9, v9, v136
	v_mul_f32_e32 v9, v9, v57
	v_fma_f32 v9, v9, v105, v73
	v_mul_f32_e32 v10, v10, v136
	v_mul_f32_e32 v10, v10, v58
	v_fma_f32 v10, v10, v106, v74
	v_mul_f32_e32 v11, v11, v136
	v_mul_f32_e32 v11, v11, v59
	v_fma_f32 v11, v11, v107, v75
	v_cvt_pk_bf16_f32 v138, v8, v9
	v_cvt_pk_bf16_f32 v139, v10, v11
	global_store_dwordx2 v137, v[138:139], s[48:49] offset:512
	v_mul_f32_e32 v12, v12, v136
	v_mul_f32_e32 v12, v12, v60
	v_fma_f32 v12, v12, v108, v76
	v_mul_f32_e32 v13, v13, v136
	v_mul_f32_e32 v13, v13, v61
	v_fma_f32 v13, v13, v109, v77
	v_mul_f32_e32 v14, v14, v136
	v_mul_f32_e32 v14, v14, v62
	v_fma_f32 v14, v14, v110, v78
	v_mul_f32_e32 v15, v15, v136
	v_mul_f32_e32 v15, v15, v63
	v_fma_f32 v15, v15, v111, v79
	v_cvt_pk_bf16_f32 v138, v12, v13
	v_cvt_pk_bf16_f32 v139, v14, v15
	global_store_dwordx2 v137, v[138:139], s[48:49] offset:1024
	v_mul_f32_e32 v16, v16, v136
	v_mul_f32_e32 v16, v16, v64
	v_fma_f32 v16, v16, v112, v80
	v_mul_f32_e32 v17, v17, v136
	v_mul_f32_e32 v17, v17, v65
	v_fma_f32 v17, v17, v113, v81
	v_mul_f32_e32 v18, v18, v136
	v_mul_f32_e32 v18, v18, v66
	v_fma_f32 v18, v18, v114, v82
	v_mul_f32_e32 v19, v19, v136
	v_mul_f32_e32 v19, v19, v67
	v_fma_f32 v19, v19, v115, v83
	v_cvt_pk_bf16_f32 v138, v16, v17
	v_cvt_pk_bf16_f32 v139, v18, v19
	global_store_dwordx2 v137, v[138:139], s[48:49] offset:1536
	s_add_u32 s48, s48, 0x400000
	s_addc_u32 s49, s49, 0
	s_waitcnt vmcnt(24)
	v_mul_f32_e32 v133, v20, v20
	v_fmac_f32_e32 v133, v21, v21
	v_fmac_f32_e32 v133, v22, v22
	v_fmac_f32_e32 v133, v23, v23
	v_fmac_f32_e32 v133, v24, v24
	v_fmac_f32_e32 v133, v25, v25
	v_fmac_f32_e32 v133, v26, v26
	v_fmac_f32_e32 v133, v27, v27
	v_fmac_f32_e32 v133, v28, v28
	v_fmac_f32_e32 v133, v29, v29
	v_fmac_f32_e32 v133, v30, v30
	v_fmac_f32_e32 v133, v31, v31
	v_fmac_f32_e32 v133, v32, v32
	v_fmac_f32_e32 v133, v33, v33
	v_fmac_f32_e32 v133, v34, v34
	v_fmac_f32_e32 v133, v35, v35
	s_nop 1
	v_add_f32_dpp v133, v133, v133 row_shr:1 row_mask:0xf bank_mask:0xf bound_ctrl:0
	s_nop 1
	v_add_f32_dpp v133, v133, v133 row_shr:2 row_mask:0xf bank_mask:0xf bound_ctrl:0
	s_nop 1
	v_add_f32_dpp v133, v133, v133 row_shr:4 row_mask:0xf bank_mask:0xf bound_ctrl:0
	s_nop 1
	v_add_f32_dpp v133, v133, v133 row_shr:8 row_mask:0xf bank_mask:0xf bound_ctrl:0
	s_nop 1
	v_readlane_b32 s35, v133, 15
	v_readlane_b32 s42, v133, 31
	v_readlane_b32 s43, v133, 47
	v_readlane_b32 s54, v133, 63
	v_mov_b32_e32 v135, s35
	v_add_f32_e32 v135, s42, v135
	v_add_f32_e32 v135, s43, v135
	v_add_f32_e32 v135, s54, v135
	v_mov_b32_e32 v136, 0x358637bd
	v_fmac_f32_e32 v136, 0x3a800000, v135
	v_rsq_f32_e32 v136, v136
	s_nop 0
	v_mul_f32_e32 v20, v20, v136
	v_mul_f32_e32 v20, v20, v52
	v_fma_f32 v20, v20, v100, v68
	v_mul_f32_e32 v21, v21, v136
	v_mul_f32_e32 v21, v21, v53
	v_fma_f32 v21, v21, v101, v69
	v_mul_f32_e32 v22, v22, v136
	v_mul_f32_e32 v22, v22, v54
	v_fma_f32 v22, v22, v102, v70
	v_mul_f32_e32 v23, v23, v136
	v_mul_f32_e32 v23, v23, v55
	v_fma_f32 v23, v23, v103, v71
	v_cvt_pk_bf16_f32 v138, v20, v21
	v_cvt_pk_bf16_f32 v139, v22, v23
	global_store_dwordx2 v137, v[138:139], s[48:49] offset:0
	v_mul_f32_e32 v24, v24, v136
	v_mul_f32_e32 v24, v24, v56
	v_fma_f32 v24, v24, v104, v72
	v_mul_f32_e32 v25, v25, v136
	v_mul_f32_e32 v25, v25, v57
	v_fma_f32 v25, v25, v105, v73
	v_mul_f32_e32 v26, v26, v136
	v_mul_f32_e32 v26, v26, v58
	v_fma_f32 v26, v26, v106, v74
	v_mul_f32_e32 v27, v27, v136
	v_mul_f32_e32 v27, v27, v59
	v_fma_f32 v27, v27, v107, v75
	v_cvt_pk_bf16_f32 v138, v24, v25
	v_cvt_pk_bf16_f32 v139, v26, v27
	global_store_dwordx2 v137, v[138:139], s[48:49] offset:512
	v_mul_f32_e32 v28, v28, v136
	v_mul_f32_e32 v28, v28, v60
	v_fma_f32 v28, v28, v108, v76
	v_mul_f32_e32 v29, v29, v136
	v_mul_f32_e32 v29, v29, v61
	v_fma_f32 v29, v29, v109, v77
	v_mul_f32_e32 v30, v30, v136
	v_mul_f32_e32 v30, v30, v62
	v_fma_f32 v30, v30, v110, v78
	v_mul_f32_e32 v31, v31, v136
	v_mul_f32_e32 v31, v31, v63
	v_fma_f32 v31, v31, v111, v79
	v_cvt_pk_bf16_f32 v138, v28, v29
	v_cvt_pk_bf16_f32 v139, v30, v31
	global_store_dwordx2 v137, v[138:139], s[48:49] offset:1024
	v_mul_f32_e32 v32, v32, v136
	v_mul_f32_e32 v32, v32, v64
	v_fma_f32 v32, v32, v112, v80
	v_mul_f32_e32 v33, v33, v136
	v_mul_f32_e32 v33, v33, v65
	v_fma_f32 v33, v33, v113, v81
	v_mul_f32_e32 v34, v34, v136
	v_mul_f32_e32 v34, v34, v66
	v_fma_f32 v34, v34, v114, v82
	v_mul_f32_e32 v35, v35, v136
	v_mul_f32_e32 v35, v35, v67
	v_fma_f32 v35, v35, v115, v83
	v_cvt_pk_bf16_f32 v138, v32, v33
	v_cvt_pk_bf16_f32 v139, v34, v35
	global_store_dwordx2 v137, v[138:139], s[48:49] offset:1536
	s_add_u32 s48, s48, 0x400000
	s_addc_u32 s49, s49, 0
	s_waitcnt vmcnt(20)
	v_mul_f32_e32 v133, v36, v36
	v_fmac_f32_e32 v133, v37, v37
	v_fmac_f32_e32 v133, v38, v38
	v_fmac_f32_e32 v133, v39, v39
	v_fmac_f32_e32 v133, v40, v40
	v_fmac_f32_e32 v133, v41, v41
	v_fmac_f32_e32 v133, v42, v42
	v_fmac_f32_e32 v133, v43, v43
	v_fmac_f32_e32 v133, v44, v44
	v_fmac_f32_e32 v133, v45, v45
	v_fmac_f32_e32 v133, v46, v46
	v_fmac_f32_e32 v133, v47, v47
	v_fmac_f32_e32 v133, v48, v48
	v_fmac_f32_e32 v133, v49, v49
	v_fmac_f32_e32 v133, v50, v50
	v_fmac_f32_e32 v133, v51, v51
	s_nop 1
	v_add_f32_dpp v133, v133, v133 row_shr:1 row_mask:0xf bank_mask:0xf bound_ctrl:0
	s_nop 1
	v_add_f32_dpp v133, v133, v133 row_shr:2 row_mask:0xf bank_mask:0xf bound_ctrl:0
	s_nop 1
	v_add_f32_dpp v133, v133, v133 row_shr:4 row_mask:0xf bank_mask:0xf bound_ctrl:0
	s_nop 1
	v_add_f32_dpp v133, v133, v133 row_shr:8 row_mask:0xf bank_mask:0xf bound_ctrl:0
	s_nop 1
	v_readlane_b32 s35, v133, 15
	v_readlane_b32 s42, v133, 31
	v_readlane_b32 s43, v133, 47
	v_readlane_b32 s54, v133, 63
	v_mov_b32_e32 v135, s35
	v_add_f32_e32 v135, s42, v135
	v_add_f32_e32 v135, s43, v135
	v_add_f32_e32 v135, s54, v135
	v_mov_b32_e32 v136, 0x358637bd
	v_fmac_f32_e32 v136, 0x3a800000, v135
	v_rsq_f32_e32 v136, v136
	s_nop 0
	v_mul_f32_e32 v36, v36, v136
	v_mul_f32_e32 v36, v36, v52
	v_fma_f32 v36, v36, v116, v84
	v_mul_f32_e32 v37, v37, v136
	v_mul_f32_e32 v37, v37, v53
	v_fma_f32 v37, v37, v117, v85
	v_mul_f32_e32 v38, v38, v136
	v_mul_f32_e32 v38, v38, v54
	v_fma_f32 v38, v38, v118, v86
	v_mul_f32_e32 v39, v39, v136
	v_mul_f32_e32 v39, v39, v55
	v_fma_f32 v39, v39, v119, v87
	v_cvt_pk_bf16_f32 v138, v36, v37
	v_cvt_pk_bf16_f32 v139, v38, v39
	global_store_dwordx2 v137, v[138:139], s[48:49] offset:0
	v_mul_f32_e32 v40, v40, v136
	v_mul_f32_e32 v40, v40, v56
	v_fma_f32 v40, v40, v120, v88
	v_mul_f32_e32 v41, v41, v136
	v_mul_f32_e32 v41, v41, v57
	v_fma_f32 v41, v41, v121, v89
	v_mul_f32_e32 v42, v42, v136
	v_mul_f32_e32 v42, v42, v58
	v_fma_f32 v42, v42, v122, v90
	v_mul_f32_e32 v43, v43, v136
	v_mul_f32_e32 v43, v43, v59
	v_fma_f32 v43, v43, v123, v91
	v_cvt_pk_bf16_f32 v138, v40, v41
	v_cvt_pk_bf16_f32 v139, v42, v43
	global_store_dwordx2 v137, v[138:139], s[48:49] offset:512
	v_mul_f32_e32 v44, v44, v136
	v_mul_f32_e32 v44, v44, v60
	v_fma_f32 v44, v44, v124, v92
	v_mul_f32_e32 v45, v45, v136
	v_mul_f32_e32 v45, v45, v61
	v_fma_f32 v45, v45, v125, v93
	v_mul_f32_e32 v46, v46, v136
	v_mul_f32_e32 v46, v46, v62
	v_fma_f32 v46, v46, v126, v94
	v_mul_f32_e32 v47, v47, v136
	v_mul_f32_e32 v47, v47, v63
	v_fma_f32 v47, v47, v127, v95
	v_cvt_pk_bf16_f32 v138, v44, v45
	v_cvt_pk_bf16_f32 v139, v46, v47
	global_store_dwordx2 v137, v[138:139], s[48:49] offset:1024
	v_mul_f32_e32 v48, v48, v136
	v_mul_f32_e32 v48, v48, v64
	v_fma_f32 v48, v48, v128, v96
	v_mul_f32_e32 v49, v49, v136
	v_mul_f32_e32 v49, v49, v65
	v_fma_f32 v49, v49, v129, v97
	v_mul_f32_e32 v50, v50, v136
	v_mul_f32_e32 v50, v50, v66
	v_fma_f32 v50, v50, v130, v98
	v_mul_f32_e32 v51, v51, v136
	v_mul_f32_e32 v51, v51, v67
	v_fma_f32 v51, v51, v131, v99
	v_cvt_pk_bf16_f32 v138, v48, v49
	v_cvt_pk_bf16_f32 v139, v50, v51
	global_store_dwordx2 v137, v[138:139], s[48:49] offset:1536
	s_waitcnt vmcnt(0)
	s_branch .LBB0_854
.Lnm1_entry:
	v_and_b32_e32 v134, 63, v206
	v_lshrrev_b32_e32 v135, 6, v206
	v_lshlrev_b32_e32 v132, 4, v134
	v_readfirstlane_b32 s40, v135
	s_lshl_b32 s41, s63, 3
	s_add_u32 s41, s41, s40
	s_add_u32 s44, s96, 0x7c84000
	s_addc_u32 s45, s97, 0
	s_add_u32 s46, s44, 0x1000000
	s_addc_u32 s47, s45, 0
	s_lshl_b32 s42, s41, 12
	s_add_u32 s48, s44, s42
	s_addc_u32 s49, s45, 0
	s_add_u32 s50, s48, 0x800000
	s_addc_u32 s51, s49, 0
	s_add_u32 s52, s46, s42
	s_addc_u32 s53, s47, 0
	global_load_dwordx4 v[4:7], v132, s[48:49]
	global_load_dwordx4 v[8:11], v132, s[48:49] offset:1024
	global_load_dwordx4 v[12:15], v132, s[48:49] offset:2048
	global_load_dwordx4 v[16:19], v132, s[48:49] offset:3072
	global_load_dwordx4 v[20:23], v132, s[50:51]
	global_load_dwordx4 v[24:27], v132, s[50:51] offset:1024
	global_load_dwordx4 v[28:31], v132, s[50:51] offset:2048
	global_load_dwordx4 v[32:35], v132, s[50:51] offset:3072
	global_load_dwordx4 v[36:39], v132, s[52:53]
	global_load_dwordx4 v[40:43], v132, s[52:53] offset:1024
	global_load_dwordx4 v[44:47], v132, s[52:53] offset:2048
	global_load_dwordx4 v[48:51], v132, s[52:53] offset:3072
	v_readlane_b32 s54, v237, 13
	v_readlane_b32 s55, v237, 14
	s_lshl_b32 s42, s36, 12
	s_add_u32 s54, s54, s42
	s_addc_u32 s55, s55, 0
	global_load_dwordx4 v[52:55], v132, s[54:55]
	global_load_dwordx4 v[56:59], v132, s[54:55] offset:1024
	global_load_dwordx4 v[60:63], v132, s[54:55] offset:2048
	global_load_dwordx4 v[64:67], v132, s[54:55] offset:3072
	s_mul_i32 s42, s36, 0x12000
	s_add_u32 s42, s42, 0x2e03000
	s_add_u32 s56, s96, s42
	s_addc_u32 s57, s97, 0
	s_lshr_b32 s42, s41, 10
	s_add_u32 s42, s42, 1
	s_mul_i32 s42, s42, 0x6000
	s_add_u32 s58, s56, s42
	s_addc_u32 s59, s57, 0
	global_load_dwordx4 v[68:71], v132, s[56:57]
	global_load_dwordx4 v[72:75], v132, s[56:57] offset:1024
	global_load_dwordx4 v[76:79], v132, s[56:57] offset:2048
	global_load_dwordx4 v[80:83], v132, s[56:57] offset:3072
	s_add_u32 s56, s56, 0x1000
	s_addc_u32 s57, s57, 0
	global_load_dwordx4 v[100:103], v132, s[56:57]
	global_load_dwordx4 v[104:107], v132, s[56:57] offset:1024
	global_load_dwordx4 v[108:111], v132, s[56:57] offset:2048
	global_load_dwordx4 v[112:115], v132, s[56:57] offset:3072
	global_load_dwordx4 v[84:87], v132, s[58:59]
	global_load_dwordx4 v[88:91], v132, s[58:59] offset:1024
	global_load_dwordx4 v[92:95], v132, s[58:59] offset:2048
	global_load_dwordx4 v[96:99], v132, s[58:59] offset:3072
	s_add_u32 s58, s58, 0x1000
	s_addc_u32 s59, s59, 0
	global_load_dwordx4 v[116:119], v132, s[58:59]
	global_load_dwordx4 v[120:123], v132, s[58:59] offset:1024
	global_load_dwordx4 v[124:127], v132, s[58:59] offset:2048
	global_load_dwordx4 v[128:131], v132, s[58:59] offset:3072
	v_lshlrev_b32_e32 v137, 3, v134
	s_lshl_b32 s42, s41, 11
	s_add_u32 s42, s42, 0x2e24000
	s_add_u32 s48, s96, s42
	s_addc_u32 s49, s97, 0
	s_waitcnt vmcnt(28)
	v_mul_f32_e32 v133, v4, v4
	v_fmac_f32_e32 v133, v5, v5
	v_fmac_f32_e32 v133, v6, v6
	v_fmac_f32_e32 v133, v7, v7
	v_fmac_f32_e32 v133, v8, v8
	v_fmac_f32_e32 v133, v9, v9
	v_fmac_f32_e32 v133, v10, v10
	v_fmac_f32_e32 v133, v11, v11
	v_fmac_f32_e32 v133, v12, v12
	v_fmac_f32_e32 v133, v13, v13
	v_fmac_f32_e32 v133, v14, v14
	v_fmac_f32_e32 v133, v15, v15
	v_fmac_f32_e32 v133, v16, v16
	v_fmac_f32_e32 v133, v17, v17
	v_fmac_f32_e32 v133, v18, v18
	v_fmac_f32_e32 v133, v19, v19
	s_nop 1
	v_add_f32_dpp v133, v133, v133 row_shr:1 row_mask:0xf bank_mask:0xf bound_ctrl:0
	s_nop 1
	v_add_f32_dpp v133, v133, v133 row_shr:2 row_mask:0xf bank_mask:0xf bound_ctrl:0
	s_nop 1
	v_add_f32_dpp v133, v133, v133 row_shr:4 row_mask:0xf bank_mask:0xf bound_ctrl:0
	s_nop 1
	v_add_f32_dpp v133, v133, v133 row_shr:8 row_mask:0xf bank_mask:0xf bound_ctrl:0
	s_nop 1
	v_readlane_b32 s35, v133, 15
	v_readlane_b32 s42, v133, 31
	v_readlane_b32 s43, v133, 47
	v_readlane_b32 s54, v133, 63
	v_mov_b32_e32 v135, s35
	v_add_f32_e32 v135, s42, v135
	v_add_f32_e32 v135, s43, v135
	v_add_f32_e32 v135, s54, v135
	v_mov_b32_e32 v136, 0x358637bd
	v_fmac_f32_e32 v136, 0x3a800000, v135
	v_rsq_f32_e32 v136, v136
	s_nop 0
	s_waitcnt vmcnt(0)
	v_add_f32_e32 v100, 1.0, v100
	v_add_f32_e32 v101, 1.0, v101
	v_add_f32_e32 v102, 1.0, v102
	v_add_f32_e32 v103, 1.0, v103
	v_add_f32_e32 v104, 1.0, v104
	v_add_f32_e32 v105, 1.0, v105
	v_add_f32_e32 v106, 1.0, v106
	v_add_f32_e32 v107, 1.0, v107
	v_add_f32_e32 v108, 1.0, v108
	v_add_f32_e32 v109, 1.0, v109
	v_add_f32_e32 v110, 1.0, v110
	v_add_f32_e32 v111, 1.0, v111
	v_add_f32_e32 v112, 1.0, v112
	v_add_f32_e32 v113, 1.0, v113
	v_add_f32_e32 v114, 1.0, v114
	v_add_f32_e32 v115, 1.0, v115
	v_add_f32_e32 v116, 1.0, v116
	v_add_f32_e32 v117, 1.0, v117
	v_add_f32_e32 v118, 1.0, v118
	v_add_f32_e32 v119, 1.0, v119
	v_add_f32_e32 v120, 1.0, v120
	v_add_f32_e32 v121, 1.0, v121
	v_add_f32_e32 v122, 1.0, v122
	v_add_f32_e32 v123, 1.0, v123
	v_add_f32_e32 v124, 1.0, v124
	v_add_f32_e32 v125, 1.0, v125
	v_add_f32_e32 v126, 1.0, v126
	v_add_f32_e32 v127, 1.0, v127
	v_add_f32_e32 v128, 1.0, v128
	v_add_f32_e32 v129, 1.0, v129
	v_add_f32_e32 v130, 1.0, v130
	v_add_f32_e32 v131, 1.0, v131
	v_mul_f32_e32 v4, v4, v136
	v_mul_f32_e32 v4, v4, v52
	v_fma_f32 v4, v4, v100, v68
	v_mul_f32_e32 v5, v5, v136
	v_mul_f32_e32 v5, v5, v53
	v_fma_f32 v5, v5, v101, v69
	v_mul_f32_e32 v6, v6, v136
	v_mul_f32_e32 v6, v6, v54
	v_fma_f32 v6, v6, v102, v70
	v_mul_f32_e32 v7, v7, v136
	v_mul_f32_e32 v7, v7, v55
	v_fma_f32 v7, v7, v103, v71
	v_cvt_pk_bf16_f32 v138, v4, v5
	v_cvt_pk_bf16_f32 v139, v6, v7
	global_store_dwordx2 v137, v[138:139], s[48:49] offset:0
	v_mul_f32_e32 v8, v8, v136
	v_mul_f32_e32 v8, v8, v56
	v_fma_f32 v8, v8, v104, v72
	v_mul_f32_e32 v9, v9, v136
	v_mul_f32_e32 v9, v9, v57
	v_fma_f32 v9, v9, v105, v73
	v_mul_f32_e32 v10, v10, v136
	v_mul_f32_e32 v10, v10, v58
	v_fma_f32 v10, v10, v106, v74
	v_mul_f32_e32 v11, v11, v136
	v_mul_f32_e32 v11, v11, v59
	v_fma_f32 v11, v11, v107, v75
	v_cvt_pk_bf16_f32 v138, v8, v9
	v_cvt_pk_bf16_f32 v139, v10, v11
	global_store_dwordx2 v137, v[138:139], s[48:49] offset:512
	v_mul_f32_e32 v12, v12, v136
	v_mul_f32_e32 v12, v12, v60
	v_fma_f32 v12, v12, v108, v76
	v_mul_f32_e32 v13, v13, v136
	v_mul_f32_e32 v13, v13, v61
	v_fma_f32 v13, v13, v109, v77
	v_mul_f32_e32 v14, v14, v136
	v_mul_f32_e32 v14, v14, v62
	v_fma_f32 v14, v14, v110, v78
	v_mul_f32_e32 v15, v15, v136
	v_mul_f32_e32 v15, v15, v63
	v_fma_f32 v15, v15, v111, v79
	v_cvt_pk_bf16_f32 v138, v12, v13
	v_cvt_pk_bf16_f32 v139, v14, v15
	global_store_dwordx2 v137, v[138:139], s[48:49] offset:1024
	v_mul_f32_e32 v16, v16, v136
	v_mul_f32_e32 v16, v16, v64
	v_fma_f32 v16, v16, v112, v80
	v_mul_f32_e32 v17, v17, v136
	v_mul_f32_e32 v17, v17, v65
	v_fma_f32 v17, v17, v113, v81
	v_mul_f32_e32 v18, v18, v136
	v_mul_f32_e32 v18, v18, v66
	v_fma_f32 v18, v18, v114, v82
	v_mul_f32_e32 v19, v19, v136
	v_mul_f32_e32 v19, v19, v67
	v_fma_f32 v19, v19, v115, v83
	v_cvt_pk_bf16_f32 v138, v16, v17
	v_cvt_pk_bf16_f32 v139, v18, v19
	global_store_dwordx2 v137, v[138:139], s[48:49] offset:1536
	s_add_u32 s48, s48, 0x400000
	s_addc_u32 s49, s49, 0
	s_waitcnt vmcnt(24)
	v_mul_f32_e32 v133, v20, v20
	v_fmac_f32_e32 v133, v21, v21
	v_fmac_f32_e32 v133, v22, v22
	v_fmac_f32_e32 v133, v23, v23
	v_fmac_f32_e32 v133, v24, v24
	v_fmac_f32_e32 v133, v25, v25
	v_fmac_f32_e32 v133, v26, v26
	v_fmac_f32_e32 v133, v27, v27
	v_fmac_f32_e32 v133, v28, v28
	v_fmac_f32_e32 v133, v29, v29
	v_fmac_f32_e32 v133, v30, v30
	v_fmac_f32_e32 v133, v31, v31
	v_fmac_f32_e32 v133, v32, v32
	v_fmac_f32_e32 v133, v33, v33
	v_fmac_f32_e32 v133, v34, v34
	v_fmac_f32_e32 v133, v35, v35
	s_nop 1
	v_add_f32_dpp v133, v133, v133 row_shr:1 row_mask:0xf bank_mask:0xf bound_ctrl:0
	s_nop 1
	v_add_f32_dpp v133, v133, v133 row_shr:2 row_mask:0xf bank_mask:0xf bound_ctrl:0
	s_nop 1
	v_add_f32_dpp v133, v133, v133 row_shr:4 row_mask:0xf bank_mask:0xf bound_ctrl:0
	s_nop 1
	v_add_f32_dpp v133, v133, v133 row_shr:8 row_mask:0xf bank_mask:0xf bound_ctrl:0
	s_nop 1
	v_readlane_b32 s35, v133, 15
	v_readlane_b32 s42, v133, 31
	v_readlane_b32 s43, v133, 47
	v_readlane_b32 s54, v133, 63
	v_mov_b32_e32 v135, s35
	v_add_f32_e32 v135, s42, v135
	v_add_f32_e32 v135, s43, v135
	v_add_f32_e32 v135, s54, v135
	v_mov_b32_e32 v136, 0x358637bd
	v_fmac_f32_e32 v136, 0x3a800000, v135
	v_rsq_f32_e32 v136, v136
	s_nop 0
	v_mul_f32_e32 v20, v20, v136
	v_mul_f32_e32 v20, v20, v52
	v_fma_f32 v20, v20, v100, v68
	v_mul_f32_e32 v21, v21, v136
	v_mul_f32_e32 v21, v21, v53
	v_fma_f32 v21, v21, v101, v69
	v_mul_f32_e32 v22, v22, v136
	v_mul_f32_e32 v22, v22, v54
	v_fma_f32 v22, v22, v102, v70
	v_mul_f32_e32 v23, v23, v136
	v_mul_f32_e32 v23, v23, v55
	v_fma_f32 v23, v23, v103, v71
	v_cvt_pk_bf16_f32 v138, v20, v21
	v_cvt_pk_bf16_f32 v139, v22, v23
	global_store_dwordx2 v137, v[138:139], s[48:49] offset:0
	v_mul_f32_e32 v24, v24, v136
	v_mul_f32_e32 v24, v24, v56
	v_fma_f32 v24, v24, v104, v72
	v_mul_f32_e32 v25, v25, v136
	v_mul_f32_e32 v25, v25, v57
	v_fma_f32 v25, v25, v105, v73
	v_mul_f32_e32 v26, v26, v136
	v_mul_f32_e32 v26, v26, v58
	v_fma_f32 v26, v26, v106, v74
	v_mul_f32_e32 v27, v27, v136
	v_mul_f32_e32 v27, v27, v59
	v_fma_f32 v27, v27, v107, v75
	v_cvt_pk_bf16_f32 v138, v24, v25
	v_cvt_pk_bf16_f32 v139, v26, v27
	global_store_dwordx2 v137, v[138:139], s[48:49] offset:512
	v_mul_f32_e32 v28, v28, v136
	v_mul_f32_e32 v28, v28, v60
	v_fma_f32 v28, v28, v108, v76
	v_mul_f32_e32 v29, v29, v136
	v_mul_f32_e32 v29, v29, v61
	v_fma_f32 v29, v29, v109, v77
	v_mul_f32_e32 v30, v30, v136
	v_mul_f32_e32 v30, v30, v62
	v_fma_f32 v30, v30, v110, v78
	v_mul_f32_e32 v31, v31, v136
	v_mul_f32_e32 v31, v31, v63
	v_fma_f32 v31, v31, v111, v79
	v_cvt_pk_bf16_f32 v138, v28, v29
	v_cvt_pk_bf16_f32 v139, v30, v31
	global_store_dwordx2 v137, v[138:139], s[48:49] offset:1024
	v_mul_f32_e32 v32, v32, v136
	v_mul_f32_e32 v32, v32, v64
	v_fma_f32 v32, v32, v112, v80
	v_mul_f32_e32 v33, v33, v136
	v_mul_f32_e32 v33, v33, v65
	v_fma_f32 v33, v33, v113, v81
	v_mul_f32_e32 v34, v34, v136
	v_mul_f32_e32 v34, v34, v66
	v_fma_f32 v34, v34, v114, v82
	v_mul_f32_e32 v35, v35, v136
	v_mul_f32_e32 v35, v35, v67
	v_fma_f32 v35, v35, v115, v83
	v_cvt_pk_bf16_f32 v138, v32, v33
	v_cvt_pk_bf16_f32 v139, v34, v35
	global_store_dwordx2 v137, v[138:139], s[48:49] offset:1536
	s_add_u32 s48, s48, 0x400000
	s_addc_u32 s49, s49, 0
	s_waitcnt vmcnt(20)
	v_mul_f32_e32 v133, v36, v36
	v_fmac_f32_e32 v133, v37, v37
	v_fmac_f32_e32 v133, v38, v38
	v_fmac_f32_e32 v133, v39, v39
	v_fmac_f32_e32 v133, v40, v40
	v_fmac_f32_e32 v133, v41, v41
	v_fmac_f32_e32 v133, v42, v42
	v_fmac_f32_e32 v133, v43, v43
	v_fmac_f32_e32 v133, v44, v44
	v_fmac_f32_e32 v133, v45, v45
	v_fmac_f32_e32 v133, v46, v46
	v_fmac_f32_e32 v133, v47, v47
	v_fmac_f32_e32 v133, v48, v48
	v_fmac_f32_e32 v133, v49, v49
	v_fmac_f32_e32 v133, v50, v50
	v_fmac_f32_e32 v133, v51, v51
	s_nop 1
	v_add_f32_dpp v133, v133, v133 row_shr:1 row_mask:0xf bank_mask:0xf bound_ctrl:0
	s_nop 1
	v_add_f32_dpp v133, v133, v133 row_shr:2 row_mask:0xf bank_mask:0xf bound_ctrl:0
	s_nop 1
	v_add_f32_dpp v133, v133, v133 row_shr:4 row_mask:0xf bank_mask:0xf bound_ctrl:0
	s_nop 1
	v_add_f32_dpp v133, v133, v133 row_shr:8 row_mask:0xf bank_mask:0xf bound_ctrl:0
	s_nop 1
	v_readlane_b32 s35, v133, 15
	v_readlane_b32 s42, v133, 31
	v_readlane_b32 s43, v133, 47
	v_readlane_b32 s54, v133, 63
	v_mov_b32_e32 v135, s35
	v_add_f32_e32 v135, s42, v135
	v_add_f32_e32 v135, s43, v135
	v_add_f32_e32 v135, s54, v135
	v_mov_b32_e32 v136, 0x358637bd
	v_fmac_f32_e32 v136, 0x3a800000, v135
	v_rsq_f32_e32 v136, v136
	s_nop 0
	v_mul_f32_e32 v36, v36, v136
	v_mul_f32_e32 v36, v36, v52
	v_fma_f32 v36, v36, v116, v84
	v_mul_f32_e32 v37, v37, v136
	v_mul_f32_e32 v37, v37, v53
	v_fma_f32 v37, v37, v117, v85
	v_mul_f32_e32 v38, v38, v136
	v_mul_f32_e32 v38, v38, v54
	v_fma_f32 v38, v38, v118, v86
	v_mul_f32_e32 v39, v39, v136
	v_mul_f32_e32 v39, v39, v55
	v_fma_f32 v39, v39, v119, v87
	v_cvt_pk_bf16_f32 v138, v36, v37
	v_cvt_pk_bf16_f32 v139, v38, v39
	global_store_dwordx2 v137, v[138:139], s[48:49] offset:0
	v_mul_f32_e32 v40, v40, v136
	v_mul_f32_e32 v40, v40, v56
	v_fma_f32 v40, v40, v120, v88
	v_mul_f32_e32 v41, v41, v136
	v_mul_f32_e32 v41, v41, v57
	v_fma_f32 v41, v41, v121, v89
	v_mul_f32_e32 v42, v42, v136
	v_mul_f32_e32 v42, v42, v58
	v_fma_f32 v42, v42, v122, v90
	v_mul_f32_e32 v43, v43, v136
	v_mul_f32_e32 v43, v43, v59
	v_fma_f32 v43, v43, v123, v91
	v_cvt_pk_bf16_f32 v138, v40, v41
	v_cvt_pk_bf16_f32 v139, v42, v43
	global_store_dwordx2 v137, v[138:139], s[48:49] offset:512
	v_mul_f32_e32 v44, v44, v136
	v_mul_f32_e32 v44, v44, v60
	v_fma_f32 v44, v44, v124, v92
	v_mul_f32_e32 v45, v45, v136
	v_mul_f32_e32 v45, v45, v61
	v_fma_f32 v45, v45, v125, v93
	v_mul_f32_e32 v46, v46, v136
	v_mul_f32_e32 v46, v46, v62
	v_fma_f32 v46, v46, v126, v94
	v_mul_f32_e32 v47, v47, v136
	v_mul_f32_e32 v47, v47, v63
	v_fma_f32 v47, v47, v127, v95
	v_cvt_pk_bf16_f32 v138, v44, v45
	v_cvt_pk_bf16_f32 v139, v46, v47
	global_store_dwordx2 v137, v[138:139], s[48:49] offset:1024
	v_mul_f32_e32 v48, v48, v136
	v_mul_f32_e32 v48, v48, v64
	v_fma_f32 v48, v48, v128, v96
	v_mul_f32_e32 v49, v49, v136
	v_mul_f32_e32 v49, v49, v65
	v_fma_f32 v49, v49, v129, v97
	v_mul_f32_e32 v50, v50, v136
	v_mul_f32_e32 v50, v50, v66
	v_fma_f32 v50, v50, v130, v98
	v_mul_f32_e32 v51, v51, v136
	v_mul_f32_e32 v51, v51, v67
	v_fma_f32 v51, v51, v131, v99
	v_cvt_pk_bf16_f32 v138, v48, v49
	v_cvt_pk_bf16_f32 v139, v50, v51
	global_store_dwordx2 v137, v[138:139], s[48:49] offset:1536
	s_waitcnt vmcnt(0)
	s_branch .LBB0_854

.Lpdt_f1:
	v_mul_f32_e32 v34, 0x3fb8aa3b, v8
	v_fma_f32 v17, v8, s84, -v34
	v_rndne_f32_e32 v18, v34
	v_fmac_f32_e32 v17, 0x32a5705f, v8
	v_sub_f32_e32 v34, v34, v18
	v_add_f32_e32 v34, v34, v17
	v_exp_f32_e32 v34, v34
	v_cvt_i32_f32_e32 v17, v18
	v_cmp_ngt_f32_e32 vcc, s87, v8
	s_nop 0
	v_ldexp_f32 v34, v34, v17
	v_cndmask_b32_e32 v34, 0, v34, vcc
	v_cmp_nlt_f32_e32 vcc, s88, v8
	s_nop 1
	v_cndmask_b32_e32 v34, v216, v34, vcc
	v_mul_f32_e64 v20, v12, -v34
	v_fma_f32 v21, v13, -v34, v20
	v_fma_f32 v22, v14, -v34, v21
	v_fma_f32 v23, v15, -v34, v22
	v_mov_b32_e32 v24, v23
	s_nop 1
	v_add_f32_dpp v24, v24, v24 row_shr:1 row_mask:0xf bank_mask:0xf bound_ctrl:0
	s_nop 1
	v_add_f32_dpp v24, v24, v24 row_shr:2 row_mask:0xf bank_mask:0xf bound_ctrl:0
	s_nop 1
	v_add_f32_dpp v24, v24, v24 row_shr:4 row_mask:0xf bank_mask:0xf bound_ctrl:0
	s_nop 1
	v_add_f32_dpp v24, v24, v24 row_shr:8 row_mask:0xf bank_mask:0xf bound_ctrl:0
	s_nop 1
	v_add_f32_dpp v24, v24, v24 row_bcast:15 row_mask:0xa bank_mask:0xf
	s_nop 1
	v_readlane_b32 s50, v24, 31
	v_readlane_b32 s51, v24, 63
	v_sub_f32_e32 v25, v24, v23
	v_mov_b32_e32 v26, s50
	s_mov_b64 vcc, exec
	s_mov_b32 exec_lo, 0
	v_mov_b32_e32 v26, s51
	s_mov_b64 exec, vcc
	v_add_f32_e32 v20, v25, v20
	v_add_f32_e32 v21, v25, v21
	v_add_f32_e32 v22, v25, v22
	v_add_f32_e32 v23, v25, v23
	v_sub_f32_e32 v28, v26, v20
	v_sub_f32_e32 v29, v26, v21
	v_sub_f32_e32 v30, v26, v22
	v_sub_f32_e32 v31, v26, v23
	v_mul_f32_e32 v28, 0x3fb8aa3b, v28
	v_mul_f32_e32 v29, 0x3fb8aa3b, v29
	v_mul_f32_e32 v30, 0x3fb8aa3b, v30
	v_mul_f32_e32 v31, 0x3fb8aa3b, v31
	v_exp_f32_e32 v28, v28
	v_exp_f32_e32 v29, v29
	v_exp_f32_e32 v30, v30
	v_exp_f32_e32 v31, v31
	s_nop 0
	v_mul_f32_e32 v28, v12, v28
	v_mul_f32_e32 v29, v13, v29
	v_mul_f32_e32 v30, v14, v30
	v_mul_f32_e32 v31, v15, v31
	s_cmp_eq_u32 s99, 0
	s_cbranch_scc1 .Lpdt_f2
	v_mov_b32_e32 v32, v12
	v_mov_b32_e32 v12, v15
	v_mov_b32_e32 v15, v32
	v_mov_b32_e32 v32, v13
	v_mov_b32_e32 v13, v14
	v_mov_b32_e32 v14, v32
	v_mov_b32_e32 v32, v20
	v_mov_b32_e32 v20, v23
	v_mov_b32_e32 v23, v32
	v_mov_b32_e32 v32, v21
	v_mov_b32_e32 v21, v22
	v_mov_b32_e32 v22, v32
	v_mov_b32_e32 v32, v28
	v_mov_b32_e32 v28, v31
	v_mov_b32_e32 v31, v32
	v_mov_b32_e32 v32, v29
	v_mov_b32_e32 v29, v30
	v_mov_b32_e32 v30, v32
